# P4 work rebalance: the 16 blocks carrying a third pool-GEMM tile skip the head-LN (ym) pass, the other 240 blocks take its rows (compact block index, stride 1920 waves); on top of v77
# speedup vs baseline: 1.0061x; 1.0061x over previous
; #define OPAQUE_TID() int tid = threadIdx.x; asm volatile("" : "+v"(tid)); const int lane = tid & 63, wave = __builtin_amdgcn_readfirstlane(tid >> 6); (void)lane; (void)wave
; #define YM_LOAD(row) do { const bf16_t* ur_ = U + (size_t)(row) * LDU + cbase; _Pragma("unroll") for (int hp = 0; hp < 2; ++hp) { \
;         nh[hp] = *(const u32x4*)(ur_ + C_V + 512 * hp); nz[hp] = *(const u32x4*)(ur_ + C_ZM + 512 * hp); } } while (0)
; __device__ __forceinline__ void ym_finalize(const Args& a, bool dry = false) {
;     OPAQUE_TID();
;     bf16_t* U = (bf16_t*)(a.ws + WS_U);
;     const int gw = blockIdx.x * 8 + wave, NGW = gridDim.x * 8;
;     const int cbase = (lane >> 5) * 256 + 8 * (lane & 31);
;     f32x4 gh[2][2];
; #pragma unroll
;     for (int hp = 0; hp < 2; ++hp) { gh[hp][0] = *(const f32x4*)(a.in[16] + cbase + 512 * hp); gh[hp][1] = *(const f32x4*)(a.in[16] + cbase + 512 * hp + 4); }
;     u32x4 nh[2], nz[2];
;     ...
;     if (gw < MT) YM_LOAD(gw);
;     for (int row = gw; row < MT; row += NGW) {
;         u32x4 ch[2], cz[2];
; #pragma unroll
;         for (int hp = 0; hp < 2; ++hp) { ch[hp] = nh[hp]; cz[hp] = nz[hp]; }
;         if (row + NGW < MT) YM_LOAD(row + NGW);
.LBB0_1128:
	s_or_b64 exec, exec, s[0:1]
	s_bitcmp0_b32 s2, 3
	s_cselect_b64 s[4:5], -1, 0
	s_and_b64 vcc, exec, s[4:5]
	s_waitcnt lgkmcnt(0)
	s_barrier
	s_cbranch_vccnz .LBB0_1134
	v_mov_b32_e32 v20, v180
	s_lshr_b32 s98, s2, 4
	s_sub_i32 s98, s2, s98
	s_add_i32 s98, s98, -1
	s_lshl_b32 s1, s98, 3
	s_movk_i32 s99, 0x780
	v_readfirstlane_b32 s0, v20
	s_ashr_i32 s0, s0, 6
	s_add_i32 s10, s0, s1
	s_cmp_gt_i32 s10, 0x83ff
	s_cbranch_scc1 .LBB0_1134
	v_lshlrev_b32_e32 v0, 3, v20
	s_mul_i32 s0, s10, 0x3800
	v_and_b32_e32 v8, 0x1f8, v0
	s_mul_hi_i32 s1, s10, 0x3800
	s_add_u32 s0, s28, s0
	s_addc_u32 s1, s29, s1
	v_lshlrev_b32_e32 v48, 1, v8
	v_mov_b32_e32 v49, 0
	v_lshlrev_b32_e32 v21, 2, v8
	v_lshl_add_u64 v[8:9], s[0:1], 0, v[48:49]
	s_movk_i32 s6, 0x3000
	v_add_co_u32_e32 v22, vcc, s6, v8
	s_movk_i32 s11, 0x1000
	s_nop 0
	v_addc_co_u32_e32 v23, vcc, 0, v9, vcc
	v_add_co_u32_e32 v24, vcc, s11, v8
	global_load_dwordx4 v[0:3], v21, s[20:21] offset:2048
	global_load_dwordx4 v[4:7], v21, s[20:21] offset:2064
	v_addc_co_u32_e32 v25, vcc, 0, v9, vcc
	global_load_dwordx4 v[36:39], v[24:25], off
	global_load_dwordx4 v[16:19], v[24:25], off offset:1024
	global_load_dwordx4 v[44:47], v[22:23], off
	global_load_dwordx4 v[40:43], v[22:23], off offset:1024
	global_load_dwordx4 v[8:11], v21, s[20:21]
	global_load_dwordx4 v[12:15], v21, s[20:21] offset:16
	v_mbcnt_hi_u32_b32 v21, -1, v181
	v_and_b32_e32 v22, 64, v21
	v_xor_b32_e32 v23, 1, v21
	v_add_u32_e32 v22, 64, v22
	v_xor_b32_e32 v24, 2, v21
	v_cmp_lt_i32_e32 vcc, v23, v22
	v_xor_b32_e32 v25, 4, v21
	v_xor_b32_e32 v26, 8, v21
	v_cndmask_b32_e32 v23, v21, v23, vcc
	v_cmp_lt_i32_e32 vcc, v24, v22
	v_xor_b32_e32 v27, 16, v21
	s_add_i32 s6, s10, s99
	v_cndmask_b32_e32 v24, v21, v24, vcc
	v_cmp_lt_i32_e32 vcc, v25, v22
	v_and_b32_e32 v20, 63, v20
	s_mul_hi_i32 s7, s6, 0x3800
	v_cndmask_b32_e32 v25, v21, v25, vcc
	v_cmp_lt_i32_e32 vcc, v26, v22
	s_mulk_i32 s6, 0x3800
	v_lshlrev_b32_e32 v48, 4, v20
	v_cndmask_b32_e32 v26, v21, v26, vcc
	v_cmp_lt_i32_e32 vcc, v27, v22
	v_lshlrev_b32_e32 v51, 2, v23
	v_lshlrev_b32_e32 v52, 2, v24
	v_cndmask_b32_e32 v21, v21, v27, vcc
	v_lshlrev_b32_e32 v53, 2, v25
	v_lshlrev_b32_e32 v54, 2, v26
	v_lshlrev_b32_e32 v55, 2, v21
	s_add_u32 s6, s28, s6
	s_mul_hi_i32 s12, s99, 0x3800
	s_mul_i32 s13, s99, 0x3800
	v_mov_b32_e32 v50, 0x358637bd
	s_mov_b32 s14, 0x800000
	s_addc_u32 s7, s29, s7
	s_waitcnt vmcnt(5)
	v_mov_b64_e32 v[28:29], v[36:37]
	s_waitcnt vmcnt(4)
	v_mov_b64_e32 v[26:27], v[18:19]
	s_waitcnt vmcnt(3)
	v_mov_b64_e32 v[20:21], v[44:45]
	s_waitcnt vmcnt(2)
	v_mov_b64_e32 v[32:33], v[40:41]
	v_mov_b64_e32 v[24:25], v[16:17]
	v_mov_b64_e32 v[30:31], v[38:39]
	v_mov_b64_e32 v[22:23], v[46:47]
	v_mov_b64_e32 v[34:35], v[42:43]
	s_branch .LBB0_1132

; #define YM_LOAD(row) do { const bf16_t* ur_ = U + (size_t)(row) * LDU + cbase; _Pragma("unroll") for (int hp = 0; hp < 2; ++hp) { \
;         nh[hp] = *(const u32x4*)(ur_ + C_V + 512 * hp); nz[hp] = *(const u32x4*)(ur_ + C_ZM + 512 * hp); } } while (0)
; __device__ __forceinline__ void ym_finalize(const Args& a, bool dry = false) {
;     ...
;     for (int row = gw; row < MT; row += NGW) {
;         u32x4 ch[2], cz[2];
; #pragma unroll
;         for (int hp = 0; hp < 2; ++hp) { ch[hp] = nh[hp]; cz[hp] = nz[hp]; }
;         if (row + NGW < MT) YM_LOAD(row + NGW);
.LBB0_1132:
	s_add_i32 s10, s10, s99
	s_cmp_gt_i32 s10, 0x83ff
	s_cselect_b64 s[8:9], -1, 0
	s_and_b64 vcc, exec, s[8:9]
	s_cbranch_vccnz .LBB0_1131
	v_lshl_add_u64 v[20:21], s[6:7], 0, v[48:49]
	v_add_co_u32_e32 v56, vcc, 0x3000, v20
	s_nop 1
	v_addc_co_u32_e32 v57, vcc, 0, v21, vcc
	v_add_co_u32_e32 v58, vcc, 0x1000, v20
	s_nop 1
	v_addc_co_u32_e32 v59, vcc, 0, v21, vcc
	global_load_dwordx4 v[20:23], v[56:57], off
	global_load_dwordx4 v[32:35], v[56:57], off offset:1024
	global_load_dwordx4 v[28:31], v[58:59], off
	global_load_dwordx4 v[24:27], v[58:59], off offset:1024
	s_branch .LBB0_1131

; #define OPAQUE_TID() int tid = threadIdx.x; asm volatile("" : "+v"(tid)); const int lane = tid & 63, wave = __builtin_amdgcn_readfirstlane(tid >> 6); (void)lane; (void)wave
; #define YM_LOAD(row) do { const bf16_t* ur_ = U + (size_t)(row) * LDU + cbase; _Pragma("unroll") for (int hp = 0; hp < 2; ++hp) { \
;         nh[hp] = *(const u32x4*)(ur_ + C_V + 512 * hp); nz[hp] = *(const u32x4*)(ur_ + C_ZM + 512 * hp); } } while (0)
; __device__ __forceinline__ void ym_finalize(const Args& a, bool dry = false) {
;     OPAQUE_TID();
;     bf16_t* U = (bf16_t*)(a.ws + WS_U);
;     const int gw = blockIdx.x * 8 + wave, NGW = gridDim.x * 8;
;     const int cbase = (lane >> 5) * 256 + 8 * (lane & 31);
;     f32x4 gh[2][2];
; #pragma unroll
;     for (int hp = 0; hp < 2; ++hp) { gh[hp][0] = *(const f32x4*)(a.in[16] + cbase + 512 * hp); gh[hp][1] = *(const f32x4*)(a.in[16] + cbase + 512 * hp + 4); }
;     u32x4 nh[2], nz[2];
;     ...
;     if (gw < MT) YM_LOAD(gw);
;     for (int row = gw; row < MT; row += NGW) {
;         u32x4 ch[2], cz[2];
; #pragma unroll
;         for (int hp = 0; hp < 2; ++hp) { ch[hp] = nh[hp]; cz[hp] = nz[hp]; }
;         if (row + NGW < MT) YM_LOAD(row + NGW);
.LBB0_1148:
	s_andn2_b64 vcc, exec, s[4:5]
	s_cbranch_vccnz .LBB0_1154
	s_and_b32 s98, s2, 15
	s_cmp_eq_u32 s98, 0
	s_cbranch_scc1 .LBB0_1154
	v_mov_b32_e32 v20, v180
	s_lshr_b32 s98, s2, 4
	s_sub_i32 s98, s2, s98
	s_add_i32 s98, s98, -1
	s_lshl_b32 s1, s98, 3
	s_movk_i32 s99, 0x780
	v_readfirstlane_b32 s0, v20
	s_ashr_i32 s0, s0, 6
	s_add_i32 s8, s0, s1
	s_cmp_gt_i32 s8, 0x83ff
	s_cbranch_scc1 .LBB0_1154
	v_lshlrev_b32_e32 v0, 3, v20
	s_mul_i32 s0, s8, 0x3800
	v_and_b32_e32 v8, 0x1f8, v0
	s_mul_hi_i32 s1, s8, 0x3800
	s_add_u32 s0, s28, s0
	s_addc_u32 s1, s29, s1
	v_lshlrev_b32_e32 v48, 1, v8
	v_mov_b32_e32 v49, 0
	v_lshlrev_b32_e32 v21, 2, v8
	v_lshl_add_u64 v[8:9], s[0:1], 0, v[48:49]
	s_movk_i32 s4, 0x3000
	v_add_co_u32_e32 v22, vcc, s4, v8
	s_movk_i32 s9, 0x1000
	s_nop 0
	v_addc_co_u32_e32 v23, vcc, 0, v9, vcc
	v_add_co_u32_e32 v24, vcc, s9, v8
	global_load_dwordx4 v[0:3], v21, s[20:21] offset:2048
	global_load_dwordx4 v[4:7], v21, s[20:21] offset:2064
	v_addc_co_u32_e32 v25, vcc, 0, v9, vcc
	global_load_dwordx4 v[36:39], v[24:25], off
	global_load_dwordx4 v[16:19], v[24:25], off offset:1024
	global_load_dwordx4 v[44:47], v[22:23], off
	global_load_dwordx4 v[40:43], v[22:23], off offset:1024
	global_load_dwordx4 v[8:11], v21, s[20:21]
	global_load_dwordx4 v[12:15], v21, s[20:21] offset:16
	v_mbcnt_hi_u32_b32 v21, -1, v181
	v_and_b32_e32 v22, 64, v21
	v_xor_b32_e32 v23, 1, v21
	v_add_u32_e32 v22, 64, v22
	v_xor_b32_e32 v24, 2, v21
	v_cmp_lt_i32_e32 vcc, v23, v22
	v_xor_b32_e32 v25, 4, v21
	v_xor_b32_e32 v26, 8, v21
	v_cndmask_b32_e32 v23, v21, v23, vcc
	v_cmp_lt_i32_e32 vcc, v24, v22
	v_xor_b32_e32 v27, 16, v21
	s_add_i32 s4, s8, s99
	v_cndmask_b32_e32 v24, v21, v24, vcc
	v_cmp_lt_i32_e32 vcc, v25, v22
	v_and_b32_e32 v20, 63, v20
	s_mul_hi_i32 s5, s4, 0x3800
	v_cndmask_b32_e32 v25, v21, v25, vcc
	v_cmp_lt_i32_e32 vcc, v26, v22
	s_mulk_i32 s4, 0x3800
	v_lshlrev_b32_e32 v48, 4, v20
	v_cndmask_b32_e32 v26, v21, v26, vcc
	v_cmp_lt_i32_e32 vcc, v27, v22
	v_lshlrev_b32_e32 v51, 2, v23
	v_lshlrev_b32_e32 v52, 2, v24
	v_cndmask_b32_e32 v21, v21, v27, vcc
	v_lshlrev_b32_e32 v53, 2, v25
	v_lshlrev_b32_e32 v54, 2, v26
	v_lshlrev_b32_e32 v55, 2, v21
	s_add_u32 s4, s28, s4
	s_mul_hi_i32 s10, s99, 0x3800
	s_mul_i32 s11, s99, 0x3800
	v_mov_b32_e32 v50, 0x358637bd
	s_mov_b32 s12, 0x800000
	s_addc_u32 s5, s29, s5
	s_waitcnt vmcnt(5)
	v_mov_b64_e32 v[28:29], v[36:37]
	s_waitcnt vmcnt(4)
	v_mov_b64_e32 v[26:27], v[18:19]
	s_waitcnt vmcnt(3)
	v_mov_b64_e32 v[20:21], v[44:45]
	s_waitcnt vmcnt(2)
	v_mov_b64_e32 v[32:33], v[40:41]
	v_mov_b64_e32 v[24:25], v[16:17]
	v_mov_b64_e32 v[30:31], v[38:39]
	v_mov_b64_e32 v[22:23], v[46:47]
	v_mov_b64_e32 v[34:35], v[42:43]
	s_branch .LBB0_1152

; #define YM_LOAD(row) do { const bf16_t* ur_ = U + (size_t)(row) * LDU + cbase; _Pragma("unroll") for (int hp = 0; hp < 2; ++hp) { \
;         nh[hp] = *(const u32x4*)(ur_ + C_V + 512 * hp); nz[hp] = *(const u32x4*)(ur_ + C_ZM + 512 * hp); } } while (0)
; __device__ __forceinline__ void ym_finalize(const Args& a, bool dry = false) {
;     ...
;     for (int row = gw; row < MT; row += NGW) {
;         u32x4 ch[2], cz[2];
; #pragma unroll
;         for (int hp = 0; hp < 2; ++hp) { ch[hp] = nh[hp]; cz[hp] = nz[hp]; }
;         if (row + NGW < MT) YM_LOAD(row + NGW);
.LBB0_1152:
	s_add_i32 s8, s8, s99
	s_cmp_gt_i32 s8, 0x83ff
	s_cselect_b64 s[6:7], -1, 0
	s_and_b64 vcc, exec, s[6:7]
	s_cbranch_vccnz .LBB0_1151
	v_lshl_add_u64 v[20:21], s[4:5], 0, v[48:49]
	v_add_co_u32_e32 v56, vcc, 0x3000, v20
	s_nop 1
	v_addc_co_u32_e32 v57, vcc, 0, v21, vcc
	v_add_co_u32_e32 v58, vcc, 0x1000, v20
	s_nop 1
	v_addc_co_u32_e32 v59, vcc, 0, v21, vcc
	global_load_dwordx4 v[20:23], v[56:57], off
	global_load_dwordx4 v[32:35], v[56:57], off offset:1024
	global_load_dwordx4 v[28:31], v[58:59], off
	global_load_dwordx4 v[24:27], v[58:59], off offset:1024
	s_branch .LBB0_1151
